# GEMM K-loops: 3/5/3/5 LDS-DMA pieces per super-phase (only the second piece of As[b][0] staged one super-phase later; SP2 waits vmcnt(7))
# baseline (speedup 1.0000x reference)
.LBB0_94:
	s_add_u32 s90, s48, 0xfffc0000
	s_addc_u32 s91, s49, -1
	v_lshl_add_u64 v[198:199], s[90:91], 0, v[148:149]
	s_mov_b32 m0, s78
	s_nop 0
	global_load_lds_dwordx4 v[198:199], off
	s_add_u32 s60, s48, 0xfffc0080
	s_addc_u32 s61, s49, -1
	s_add_i32 s88, 0, 0x10000
	s_cmp_eq_u32 s87, 12
	s_cselect_b32 vcc_hi, s59, s61
	s_cselect_b32 vcc_lo, s83, s60
	v_add_u32_e32 v2, s88, v182
	s_cselect_b32 s61, s95, s86
	s_cselect_b32 s60, s84, s85
	s_add_i32 s90, 0, 0x14000
	ds_read_b128 v[132:135], v2
	ds_read_b128 v[136:139], v2 offset:1024
	ds_read_b128 v[140:143], v2 offset:2048
	ds_read_b128 v[144:147], v2 offset:3072
	v_add_u32_e32 v2, s90, v182
	ds_read_b128 v[162:165], v2
	ds_read_b128 v[166:169], v2 offset:1024
	ds_read_b128 v[170:173], v2 offset:2048
	ds_read_b128 v[174:177], v2 offset:3072
	v_lshl_add_u64 v[198:199], s[48:49], 0, v[158:159]
	s_add_i32 m0, s73, 0xc000
	ds_read_b128 v[178:181], v185
	ds_read_b128 v[186:189], v185 offset:1024
	ds_read_b128 v[190:193], v185 offset:2048
	ds_read_b128 v[194:197], v185 offset:3072
	ds_read_b128 v[208:211], v185 offset:4096
	ds_read_b128 v[212:215], v185 offset:5120
	ds_read_b128 v[216:219], v185 offset:6144
	ds_read_b128 v[220:223], v185 offset:7168
	global_load_lds_dwordx4 v[198:199], off
	v_lshl_add_u64 v[198:199], s[48:49], 0, v[160:161]
	s_add_i32 m0, s73, 0xe000
	s_nop 0
	global_load_lds_dwordx4 v[198:199], off
	s_waitcnt vmcnt(8)
	s_waitcnt lgkmcnt(0)
	s_barrier
	s_setprio 1
	s_waitcnt lgkmcnt(0)
	v_mfma_f32_16x16x32_bf16 v[128:131], v[132:135], v[178:181], v[128:131]
	v_mfma_f32_16x16x32_bf16 v[120:123], v[140:143], v[178:181], v[120:123]
	v_mfma_f32_16x16x32_bf16 v[112:115], v[132:135], v[190:193], v[112:115]
	v_mfma_f32_16x16x32_bf16 v[84:87], v[140:143], v[190:193], v[84:87]
	v_mfma_f32_16x16x32_bf16 v[104:107], v[132:135], v[208:211], v[104:107]
	v_mfma_f32_16x16x32_bf16 v[72:75], v[140:143], v[208:211], v[72:75]
	v_mfma_f32_16x16x32_bf16 v[96:99], v[132:135], v[216:219], v[96:99]
	v_mfma_f32_16x16x32_bf16 v[88:91], v[140:143], v[216:219], v[88:91]
	v_mfma_f32_16x16x32_bf16 v[128:131], v[136:139], v[186:189], v[128:131]
	v_mfma_f32_16x16x32_bf16 v[120:123], v[144:147], v[186:189], v[120:123]
	v_mfma_f32_16x16x32_bf16 v[112:115], v[136:139], v[194:197], v[112:115]
	v_mfma_f32_16x16x32_bf16 v[84:87], v[144:147], v[194:197], v[84:87]
	v_mfma_f32_16x16x32_bf16 v[104:107], v[136:139], v[212:215], v[104:107]
	v_mfma_f32_16x16x32_bf16 v[72:75], v[144:147], v[212:215], v[72:75]
	v_mfma_f32_16x16x32_bf16 v[96:99], v[136:139], v[220:223], v[96:99]
	v_mfma_f32_16x16x32_bf16 v[88:91], v[144:147], v[220:223], v[88:91]
	s_setprio 0
	s_setprio 1
	v_mfma_f32_16x16x32_bf16 v[124:127], v[162:165], v[178:181], v[124:127]
	v_mfma_f32_16x16x32_bf16 v[116:119], v[170:173], v[178:181], v[116:119]
	v_mfma_f32_16x16x32_bf16 v[108:111], v[162:165], v[190:193], v[108:111]
	v_mfma_f32_16x16x32_bf16 v[76:79], v[170:173], v[190:193], v[76:79]
	v_mfma_f32_16x16x32_bf16 v[100:103], v[162:165], v[208:211], v[100:103]
	v_mfma_f32_16x16x32_bf16 v[68:71], v[170:173], v[208:211], v[68:71]
	v_mfma_f32_16x16x32_bf16 v[92:95], v[162:165], v[216:219], v[92:95]
	v_mfma_f32_16x16x32_bf16 v[80:83], v[170:173], v[216:219], v[80:83]
	v_mfma_f32_16x16x32_bf16 v[124:127], v[166:169], v[186:189], v[124:127]
	v_mfma_f32_16x16x32_bf16 v[116:119], v[174:177], v[186:189], v[116:119]
	v_mfma_f32_16x16x32_bf16 v[108:111], v[166:169], v[194:197], v[108:111]
	v_mfma_f32_16x16x32_bf16 v[76:79], v[174:177], v[194:197], v[76:79]
	v_mfma_f32_16x16x32_bf16 v[100:103], v[166:169], v[212:215], v[100:103]
	v_mfma_f32_16x16x32_bf16 v[68:71], v[174:177], v[212:215], v[68:71]
	v_mfma_f32_16x16x32_bf16 v[92:95], v[166:169], v[220:223], v[92:95]
	v_mfma_f32_16x16x32_bf16 v[80:83], v[174:177], v[220:223], v[80:83]
	s_setprio 0
	s_barrier
	s_add_i32 s88, s88, s72
	v_lshl_add_u64 v[198:199], s[60:61], 0, v[150:151]
	s_mov_b32 m0, s88
	ds_read_b128 v[178:181], v185 offset:16384
	ds_read_b128 v[186:189], v185 offset:17408
	ds_read_b128 v[190:193], v185 offset:18432
	ds_read_b128 v[194:197], v185 offset:19456
	ds_read_b128 v[208:211], v185 offset:20480
	ds_read_b128 v[212:215], v185 offset:21504
	ds_read_b128 v[216:219], v185 offset:22528
	ds_read_b128 v[220:223], v185 offset:23552
	global_load_lds_dwordx4 v[198:199], off
	s_add_i32 m0, s88, 0x2000
	s_add_u32 s88, s60, 0x40000
	v_lshl_add_u64 v[204:205], s[60:61], 0, v[0:1]
	s_addc_u32 s89, s61, 0
	s_add_i32 s90, s90, s72
	global_load_lds_dwordx4 v[204:205], off
	v_lshl_add_u64 v[206:207], s[88:89], 0, v[150:151]
	s_mov_b32 m0, s90
	v_lshl_add_u64 v[224:225], vcc, 0, v[148:149]
	global_load_lds_dwordx4 v[206:207], off
	v_lshl_add_u64 v[206:207], s[88:89], 0, v[0:1]
	s_add_i32 m0, s90, 0x2000
	s_nop 0
	global_load_lds_dwordx4 v[206:207], off
	v_lshl_add_u64 v[206:207], vcc, 0, v[152:153]
	s_mov_b32 m0, s73
	s_nop 0
	global_load_lds_dwordx4 v[206:207], off


	s_waitcnt vmcnt(7)
	s_waitcnt lgkmcnt(0)
	s_barrier
	s_setprio 1
	s_waitcnt lgkmcnt(0)
	v_mfma_f32_16x16x32_bf16 v[64:67], v[132:135], v[178:181], v[64:67]
	v_mfma_f32_16x16x32_bf16 v[56:59], v[140:143], v[178:181], v[56:59]
	v_mfma_f32_16x16x32_bf16 v[52:55], v[132:135], v[190:193], v[52:55]
	v_mfma_f32_16x16x32_bf16 v[20:23], v[140:143], v[190:193], v[20:23]
	v_mfma_f32_16x16x32_bf16 v[40:43], v[132:135], v[208:211], v[40:43]
	v_mfma_f32_16x16x32_bf16 v[8:11], v[140:143], v[208:211], v[8:11]
	v_mfma_f32_16x16x32_bf16 v[32:35], v[132:135], v[216:219], v[32:35]
	v_mfma_f32_16x16x32_bf16 v[24:27], v[140:143], v[216:219], v[24:27]
	v_mfma_f32_16x16x32_bf16 v[64:67], v[136:139], v[186:189], v[64:67]
	v_mfma_f32_16x16x32_bf16 v[56:59], v[144:147], v[186:189], v[56:59]
	v_mfma_f32_16x16x32_bf16 v[52:55], v[136:139], v[194:197], v[52:55]
	v_mfma_f32_16x16x32_bf16 v[20:23], v[144:147], v[194:197], v[20:23]
	v_mfma_f32_16x16x32_bf16 v[40:43], v[136:139], v[212:215], v[40:43]
	v_mfma_f32_16x16x32_bf16 v[8:11], v[144:147], v[212:215], v[8:11]
	v_mfma_f32_16x16x32_bf16 v[32:35], v[136:139], v[220:223], v[32:35]
	v_mfma_f32_16x16x32_bf16 v[24:27], v[144:147], v[220:223], v[24:27]
	s_setprio 0
	s_setprio 1
	v_mfma_f32_16x16x32_bf16 v[60:63], v[162:165], v[178:181], v[60:63]
	v_mfma_f32_16x16x32_bf16 v[48:51], v[170:173], v[178:181], v[48:51]
	v_mfma_f32_16x16x32_bf16 v[44:47], v[162:165], v[190:193], v[44:47]
	v_mfma_f32_16x16x32_bf16 v[12:15], v[170:173], v[190:193], v[12:15]
	v_mfma_f32_16x16x32_bf16 v[36:39], v[162:165], v[208:211], v[36:39]
	v_mfma_f32_16x16x32_bf16 v[4:7], v[170:173], v[208:211], v[4:7]
	v_mfma_f32_16x16x32_bf16 v[28:31], v[162:165], v[216:219], v[28:31]
	v_mfma_f32_16x16x32_bf16 v[16:19], v[170:173], v[216:219], v[16:19]
	v_mfma_f32_16x16x32_bf16 v[60:63], v[166:169], v[186:189], v[60:63]
	v_mfma_f32_16x16x32_bf16 v[48:51], v[174:177], v[186:189], v[48:51]
	v_mfma_f32_16x16x32_bf16 v[44:47], v[166:169], v[194:197], v[44:47]
	v_mfma_f32_16x16x32_bf16 v[12:15], v[174:177], v[194:197], v[12:15]
	v_mfma_f32_16x16x32_bf16 v[36:39], v[166:169], v[212:215], v[36:39]
	v_mfma_f32_16x16x32_bf16 v[4:7], v[174:177], v[212:215], v[4:7]
	v_mfma_f32_16x16x32_bf16 v[28:31], v[166:169], v[220:223], v[28:31]
	v_mfma_f32_16x16x32_bf16 v[16:19], v[174:177], v[220:223], v[16:19]
	s_setprio 0
	s_barrier
	s_add_i32 s90, 0, 0x18000
	v_add_u32_e32 v2, s90, v182
	s_add_i32 s91, 0, 0x1c000
	ds_read_b128 v[132:135], v2
	ds_read_b128 v[136:139], v2 offset:1024
	ds_read_b128 v[140:143], v2 offset:2048
	ds_read_b128 v[144:147], v2 offset:3072
	v_add_u32_e32 v2, s91, v182
	ds_read_b128 v[162:165], v2
	ds_read_b128 v[166:169], v2 offset:1024
	ds_read_b128 v[170:173], v2 offset:2048
	ds_read_b128 v[174:177], v2 offset:3072
	s_add_u32 s88, vcc_lo, 0x40000
	s_addc_u32 s89, vcc_hi, 0
	s_mov_b32 m0, s74
	s_nop 0
	global_load_lds_dwordx4 v[224:225], off
	s_mov_b32 m0, s75
	v_lshl_add_u64 v[226:227], s[88:89], 0, v[152:153]
	ds_read_b128 v[178:181], v185 offset:32768
	ds_read_b128 v[186:189], v185 offset:33792
	ds_read_b128 v[190:193], v185 offset:34816
	ds_read_b128 v[194:197], v185 offset:35840
	ds_read_b128 v[208:211], v185 offset:36864
	ds_read_b128 v[212:215], v185 offset:37888
	ds_read_b128 v[216:219], v185 offset:38912
	ds_read_b128 v[220:223], v185 offset:39936
	global_load_lds_dwordx4 v[226:227], off
	v_lshl_add_u64 v[226:227], s[88:89], 0, v[148:149]
	s_mov_b32 m0, s76
	s_nop 0
	global_load_lds_dwordx4 v[226:227], off
	s_waitcnt vmcnt(8)
	s_waitcnt lgkmcnt(0)
	s_barrier
	s_setprio 1
	s_waitcnt lgkmcnt(0)
	v_mfma_f32_16x16x32_bf16 v[128:131], v[132:135], v[178:181], v[128:131]
	v_mfma_f32_16x16x32_bf16 v[120:123], v[140:143], v[178:181], v[120:123]
	v_mfma_f32_16x16x32_bf16 v[112:115], v[132:135], v[190:193], v[112:115]
	v_mfma_f32_16x16x32_bf16 v[84:87], v[140:143], v[190:193], v[84:87]
	v_mfma_f32_16x16x32_bf16 v[104:107], v[132:135], v[208:211], v[104:107]
	v_mfma_f32_16x16x32_bf16 v[72:75], v[140:143], v[208:211], v[72:75]
	v_mfma_f32_16x16x32_bf16 v[96:99], v[132:135], v[216:219], v[96:99]
	v_mfma_f32_16x16x32_bf16 v[88:91], v[140:143], v[216:219], v[88:91]
	v_mfma_f32_16x16x32_bf16 v[128:131], v[136:139], v[186:189], v[128:131]
	v_mfma_f32_16x16x32_bf16 v[120:123], v[144:147], v[186:189], v[120:123]
	v_mfma_f32_16x16x32_bf16 v[112:115], v[136:139], v[194:197], v[112:115]
	v_mfma_f32_16x16x32_bf16 v[84:87], v[144:147], v[194:197], v[84:87]
	v_mfma_f32_16x16x32_bf16 v[104:107], v[136:139], v[212:215], v[104:107]
	v_mfma_f32_16x16x32_bf16 v[72:75], v[144:147], v[212:215], v[72:75]
	v_mfma_f32_16x16x32_bf16 v[96:99], v[136:139], v[220:223], v[96:99]
	v_mfma_f32_16x16x32_bf16 v[88:91], v[144:147], v[220:223], v[88:91]
	s_setprio 0
	s_setprio 1
	v_mfma_f32_16x16x32_bf16 v[124:127], v[162:165], v[178:181], v[124:127]
	v_mfma_f32_16x16x32_bf16 v[116:119], v[170:173], v[178:181], v[116:119]
	v_mfma_f32_16x16x32_bf16 v[108:111], v[162:165], v[190:193], v[108:111]
	v_mfma_f32_16x16x32_bf16 v[76:79], v[170:173], v[190:193], v[76:79]
	v_mfma_f32_16x16x32_bf16 v[100:103], v[162:165], v[208:211], v[100:103]
	v_mfma_f32_16x16x32_bf16 v[68:71], v[170:173], v[208:211], v[68:71]
	v_mfma_f32_16x16x32_bf16 v[92:95], v[162:165], v[216:219], v[92:95]
	v_mfma_f32_16x16x32_bf16 v[80:83], v[170:173], v[216:219], v[80:83]
	v_mfma_f32_16x16x32_bf16 v[124:127], v[166:169], v[186:189], v[124:127]
	v_mfma_f32_16x16x32_bf16 v[116:119], v[174:177], v[186:189], v[116:119]
	v_mfma_f32_16x16x32_bf16 v[108:111], v[166:169], v[194:197], v[108:111]
	v_mfma_f32_16x16x32_bf16 v[76:79], v[174:177], v[194:197], v[76:79]
	v_mfma_f32_16x16x32_bf16 v[100:103], v[166:169], v[212:215], v[100:103]
	v_mfma_f32_16x16x32_bf16 v[68:71], v[174:177], v[212:215], v[68:71]
	v_mfma_f32_16x16x32_bf16 v[92:95], v[166:169], v[220:223], v[92:95]
	v_mfma_f32_16x16x32_bf16 v[80:83], v[174:177], v[220:223], v[80:83]
	s_setprio 0
	s_barrier
	s_add_i32 s88, s90, s72
	v_lshl_add_u64 v[198:199], v[198:199], 0, s[12:13]
	s_mov_b32 m0, s88
	ds_read_b128 v[178:181], v185 offset:49152
	ds_read_b128 v[186:189], v185 offset:50176
	ds_read_b128 v[190:193], v185 offset:51200
	ds_read_b128 v[194:197], v185 offset:52224
	ds_read_b128 v[208:211], v185 offset:53248
	ds_read_b128 v[212:215], v185 offset:54272
	ds_read_b128 v[216:219], v185 offset:55296
	ds_read_b128 v[220:223], v185 offset:56320
	global_load_lds_dwordx4 v[198:199], off
	s_add_i32 m0, s88, 0x2000
	s_add_u32 s60, s60, 0x40080
	v_lshl_add_u64 v[198:199], v[204:205], 0, s[12:13]
	s_addc_u32 s61, s61, 0
	s_add_i32 s88, s91, s72
	global_load_lds_dwordx4 v[198:199], off
	v_lshl_add_u64 v[198:199], s[60:61], 0, v[150:151]
	s_mov_b32 m0, s88
	s_nop 0
	global_load_lds_dwordx4 v[198:199], off
	v_lshl_add_u64 v[198:199], s[60:61], 0, v[0:1]
	s_add_i32 m0, s88, 0x2000
	s_nop 0
	global_load_lds_dwordx4 v[198:199], off
	v_lshl_add_u64 v[198:199], v[206:207], 0, s[12:13]
	s_mov_b32 m0, s77
	s_nop 0
	global_load_lds_dwordx4 v[198:199], off


	s_waitcnt vmcnt(7)
	s_waitcnt lgkmcnt(0)
	s_barrier
	s_setprio 1
	s_waitcnt lgkmcnt(0)
	v_mfma_f32_16x16x32_bf16 v[64:67], v[132:135], v[178:181], v[64:67]
	v_mfma_f32_16x16x32_bf16 v[56:59], v[140:143], v[178:181], v[56:59]
	v_mfma_f32_16x16x32_bf16 v[52:55], v[132:135], v[190:193], v[52:55]
	v_mfma_f32_16x16x32_bf16 v[20:23], v[140:143], v[190:193], v[20:23]
	v_mfma_f32_16x16x32_bf16 v[40:43], v[132:135], v[208:211], v[40:43]
	v_mfma_f32_16x16x32_bf16 v[8:11], v[140:143], v[208:211], v[8:11]
	v_mfma_f32_16x16x32_bf16 v[32:35], v[132:135], v[216:219], v[32:35]
	v_mfma_f32_16x16x32_bf16 v[24:27], v[140:143], v[216:219], v[24:27]
	v_mfma_f32_16x16x32_bf16 v[64:67], v[136:139], v[186:189], v[64:67]
	v_mfma_f32_16x16x32_bf16 v[56:59], v[144:147], v[186:189], v[56:59]
	v_mfma_f32_16x16x32_bf16 v[52:55], v[136:139], v[194:197], v[52:55]
	v_mfma_f32_16x16x32_bf16 v[20:23], v[144:147], v[194:197], v[20:23]
	v_mfma_f32_16x16x32_bf16 v[40:43], v[136:139], v[212:215], v[40:43]
	v_mfma_f32_16x16x32_bf16 v[8:11], v[144:147], v[212:215], v[8:11]
	v_mfma_f32_16x16x32_bf16 v[32:35], v[136:139], v[220:223], v[32:35]
	v_mfma_f32_16x16x32_bf16 v[24:27], v[144:147], v[220:223], v[24:27]
	s_setprio 0
	s_setprio 1
	v_mfma_f32_16x16x32_bf16 v[60:63], v[162:165], v[178:181], v[60:63]
	v_mfma_f32_16x16x32_bf16 v[48:51], v[170:173], v[178:181], v[48:51]
	v_mfma_f32_16x16x32_bf16 v[44:47], v[162:165], v[190:193], v[44:47]
	v_mfma_f32_16x16x32_bf16 v[12:15], v[170:173], v[190:193], v[12:15]
	v_mfma_f32_16x16x32_bf16 v[36:39], v[162:165], v[208:211], v[36:39]
	v_mfma_f32_16x16x32_bf16 v[4:7], v[170:173], v[208:211], v[4:7]
	v_mfma_f32_16x16x32_bf16 v[28:31], v[162:165], v[216:219], v[28:31]
	v_mfma_f32_16x16x32_bf16 v[16:19], v[170:173], v[216:219], v[16:19]
	v_mfma_f32_16x16x32_bf16 v[60:63], v[166:169], v[186:189], v[60:63]
	v_mfma_f32_16x16x32_bf16 v[48:51], v[174:177], v[186:189], v[48:51]
	v_mfma_f32_16x16x32_bf16 v[44:47], v[166:169], v[194:197], v[44:47]
	v_mfma_f32_16x16x32_bf16 v[12:15], v[174:177], v[194:197], v[12:15]
	v_mfma_f32_16x16x32_bf16 v[36:39], v[166:169], v[212:215], v[36:39]
	v_mfma_f32_16x16x32_bf16 v[4:7], v[174:177], v[212:215], v[4:7]
	v_mfma_f32_16x16x32_bf16 v[28:31], v[166:169], v[220:223], v[28:31]
	v_mfma_f32_16x16x32_bf16 v[16:19], v[174:177], v[220:223], v[16:19]
	s_setprio 0
	s_barrier
	s_add_i32 s87, s87, 2
	s_add_u32 s48, s48, 0x100
	s_addc_u32 s49, s49, 0
	s_add_u32 s85, s85, 0x100
	s_addc_u32 s86, s86, 0
	s_cmp_gt_u32 s87, 13
	s_cbranch_scc0 .LBB0_94
	s_and_b64 vcc, exec, s[20:21]
	s_cbranch_vccz .LBB0_97
	s_barrier

.LBB0_685:
	s_add_u32 s82, s46, 0xfff80000
	s_addc_u32 s83, s47, -1
	v_lshl_add_u64 v[200:201], s[82:83], 0, v[132:133]
	s_mov_b32 m0, s72
	s_nop 0
	global_load_lds_dwordx4 v[200:201], off
	s_add_u32 s48, s46, 0xfff80080
	s_addc_u32 s49, s47, -1
	s_add_i32 s81, 0, 0x10000
	s_cmp_eq_u32 s80, 28
	s_cselect_b32 s51, s35, s49
	s_cselect_b32 s50, s76, s48
	s_cselect_b32 s49, s21, s79
	s_cselect_b32 s48, s77, s78
	s_add_i32 s84, 0, 0x14000
	v_add_u32_e32 v156, s81, v149
	v_add_u32_e32 v172, s84, v149
	ds_read_b128 v[140:143], v156
	ds_read_b128 v[144:147], v156 offset:1024
	ds_read_b128 v[152:155], v156 offset:2048
	ds_read_b128 v[156:159], v156 offset:3072
	ds_read_b128 v[160:163], v172
	ds_read_b128 v[164:167], v172 offset:1024
	ds_read_b128 v[168:171], v172 offset:2048
	ds_read_b128 v[172:175], v172 offset:3072
	v_lshl_add_u64 v[200:201], s[46:47], 0, v[136:137]
	s_add_i32 m0, s59, 0xc000
	ds_read_b128 v[176:179], v151
	ds_read_b128 v[180:183], v151 offset:1024
	ds_read_b128 v[184:187], v151 offset:2048
	ds_read_b128 v[188:191], v151 offset:3072
	ds_read_b128 v[192:195], v151 offset:4096
	ds_read_b128 v[196:199], v151 offset:5120
	ds_read_b128 v[204:207], v151 offset:6144
	ds_read_b128 v[208:211], v151 offset:7168
	global_load_lds_dwordx4 v[200:201], off
	v_lshl_add_u64 v[200:201], s[46:47], 0, v[138:139]
	s_add_i32 m0, s59, 0xe000
	s_nop 0
	global_load_lds_dwordx4 v[200:201], off
	s_waitcnt vmcnt(8)
	s_waitcnt lgkmcnt(0)
	s_barrier
	s_setprio 1
	s_waitcnt lgkmcnt(0)
	v_mfma_f32_16x16x32_bf16 v[128:131], v[140:143], v[176:179], v[128:131]
	v_mfma_f32_16x16x32_bf16 v[124:127], v[152:155], v[176:179], v[124:127]
	v_mfma_f32_16x16x32_bf16 v[112:115], v[140:143], v[184:187], v[112:115]
	v_mfma_f32_16x16x32_bf16 v[108:111], v[152:155], v[184:187], v[108:111]
	v_mfma_f32_16x16x32_bf16 v[96:99], v[140:143], v[192:195], v[96:99]
	v_mfma_f32_16x16x32_bf16 v[92:95], v[152:155], v[192:195], v[92:95]
	v_mfma_f32_16x16x32_bf16 v[80:83], v[140:143], v[204:207], v[80:83]
	v_mfma_f32_16x16x32_bf16 v[76:79], v[152:155], v[204:207], v[76:79]
	v_mfma_f32_16x16x32_bf16 v[128:131], v[144:147], v[180:183], v[128:131]
	v_mfma_f32_16x16x32_bf16 v[124:127], v[156:159], v[180:183], v[124:127]
	v_mfma_f32_16x16x32_bf16 v[112:115], v[144:147], v[188:191], v[112:115]
	v_mfma_f32_16x16x32_bf16 v[108:111], v[156:159], v[188:191], v[108:111]
	v_mfma_f32_16x16x32_bf16 v[96:99], v[144:147], v[196:199], v[96:99]
	v_mfma_f32_16x16x32_bf16 v[92:95], v[156:159], v[196:199], v[92:95]
	v_mfma_f32_16x16x32_bf16 v[80:83], v[144:147], v[208:211], v[80:83]
	v_mfma_f32_16x16x32_bf16 v[76:79], v[156:159], v[208:211], v[76:79]
	s_setprio 0
	s_setprio 1
	v_mfma_f32_16x16x32_bf16 v[120:123], v[160:163], v[176:179], v[120:123]
	v_mfma_f32_16x16x32_bf16 v[116:119], v[168:171], v[176:179], v[116:119]
	v_mfma_f32_16x16x32_bf16 v[104:107], v[160:163], v[184:187], v[104:107]
	v_mfma_f32_16x16x32_bf16 v[100:103], v[168:171], v[184:187], v[100:103]
	v_mfma_f32_16x16x32_bf16 v[88:91], v[160:163], v[192:195], v[88:91]
	v_mfma_f32_16x16x32_bf16 v[84:87], v[168:171], v[192:195], v[84:87]
	v_mfma_f32_16x16x32_bf16 v[72:75], v[160:163], v[204:207], v[72:75]
	v_mfma_f32_16x16x32_bf16 v[68:71], v[168:171], v[204:207], v[68:71]
	v_mfma_f32_16x16x32_bf16 v[120:123], v[164:167], v[180:183], v[120:123]
	v_mfma_f32_16x16x32_bf16 v[116:119], v[172:175], v[180:183], v[116:119]
	v_mfma_f32_16x16x32_bf16 v[104:107], v[164:167], v[188:191], v[104:107]
	v_mfma_f32_16x16x32_bf16 v[100:103], v[172:175], v[188:191], v[100:103]
	v_mfma_f32_16x16x32_bf16 v[88:91], v[164:167], v[196:199], v[88:91]
	v_mfma_f32_16x16x32_bf16 v[84:87], v[172:175], v[196:199], v[84:87]
	v_mfma_f32_16x16x32_bf16 v[72:75], v[164:167], v[208:211], v[72:75]
	v_mfma_f32_16x16x32_bf16 v[68:71], v[172:175], v[208:211], v[68:71]
	s_setprio 0
	s_barrier
	s_add_i32 s81, s81, s52
	v_lshl_add_u64 v[200:201], s[48:49], 0, v[2:3]
	s_mov_b32 m0, s81
	ds_read_b128 v[176:179], v151 offset:16384
	ds_read_b128 v[180:183], v151 offset:17408
	ds_read_b128 v[184:187], v151 offset:18432
	ds_read_b128 v[188:191], v151 offset:19456
	ds_read_b128 v[192:195], v151 offset:20480
	ds_read_b128 v[196:199], v151 offset:21504
	ds_read_b128 v[204:207], v151 offset:22528
	ds_read_b128 v[208:211], v151 offset:23552
	global_load_lds_dwordx4 v[200:201], off
	s_add_i32 m0, s81, 0x2000
	s_add_u32 s82, s48, 0x80000
	v_lshl_add_u64 v[212:213], s[48:49], 0, v[0:1]
	s_addc_u32 s83, s49, 0
	s_add_i32 s81, s84, s52
	global_load_lds_dwordx4 v[212:213], off
	v_lshl_add_u64 v[214:215], s[82:83], 0, v[2:3]
	s_mov_b32 m0, s81
	v_lshl_add_u64 v[216:217], s[50:51], 0, v[132:133]
	global_load_lds_dwordx4 v[214:215], off
	v_lshl_add_u64 v[214:215], s[82:83], 0, v[0:1]
	s_add_i32 m0, s81, 0x2000
	s_nop 0
	global_load_lds_dwordx4 v[214:215], off
	v_lshl_add_u64 v[214:215], s[50:51], 0, v[134:135]
	s_mov_b32 m0, s59
	s_nop 0
	global_load_lds_dwordx4 v[214:215], off


	s_waitcnt vmcnt(7)
	s_waitcnt lgkmcnt(0)
	s_barrier
	s_setprio 1
	s_waitcnt lgkmcnt(0)
	v_mfma_f32_16x16x32_bf16 v[64:67], v[140:143], v[176:179], v[64:67]
	v_mfma_f32_16x16x32_bf16 v[60:63], v[152:155], v[176:179], v[60:63]
	v_mfma_f32_16x16x32_bf16 v[48:51], v[140:143], v[184:187], v[48:51]
	v_mfma_f32_16x16x32_bf16 v[44:47], v[152:155], v[184:187], v[44:47]
	v_mfma_f32_16x16x32_bf16 v[32:35], v[140:143], v[192:195], v[32:35]
	v_mfma_f32_16x16x32_bf16 v[28:31], v[152:155], v[192:195], v[28:31]
	v_mfma_f32_16x16x32_bf16 v[16:19], v[140:143], v[204:207], v[16:19]
	v_mfma_f32_16x16x32_bf16 v[12:15], v[152:155], v[204:207], v[12:15]
	v_mfma_f32_16x16x32_bf16 v[64:67], v[144:147], v[180:183], v[64:67]
	v_mfma_f32_16x16x32_bf16 v[60:63], v[156:159], v[180:183], v[60:63]
	v_mfma_f32_16x16x32_bf16 v[48:51], v[144:147], v[188:191], v[48:51]
	v_mfma_f32_16x16x32_bf16 v[44:47], v[156:159], v[188:191], v[44:47]
	v_mfma_f32_16x16x32_bf16 v[32:35], v[144:147], v[196:199], v[32:35]
	v_mfma_f32_16x16x32_bf16 v[28:31], v[156:159], v[196:199], v[28:31]
	v_mfma_f32_16x16x32_bf16 v[16:19], v[144:147], v[208:211], v[16:19]
	v_mfma_f32_16x16x32_bf16 v[12:15], v[156:159], v[208:211], v[12:15]
	s_setprio 0
	s_setprio 1
	v_mfma_f32_16x16x32_bf16 v[56:59], v[160:163], v[176:179], v[56:59]
	v_mfma_f32_16x16x32_bf16 v[52:55], v[168:171], v[176:179], v[52:55]
	v_mfma_f32_16x16x32_bf16 v[40:43], v[160:163], v[184:187], v[40:43]
	v_mfma_f32_16x16x32_bf16 v[36:39], v[168:171], v[184:187], v[36:39]
	v_mfma_f32_16x16x32_bf16 v[24:27], v[160:163], v[192:195], v[24:27]
	v_mfma_f32_16x16x32_bf16 v[20:23], v[168:171], v[192:195], v[20:23]
	v_mfma_f32_16x16x32_bf16 v[8:11], v[160:163], v[204:207], v[8:11]
	v_mfma_f32_16x16x32_bf16 v[4:7], v[168:171], v[204:207], v[4:7]
	v_mfma_f32_16x16x32_bf16 v[56:59], v[164:167], v[180:183], v[56:59]
	v_mfma_f32_16x16x32_bf16 v[52:55], v[172:175], v[180:183], v[52:55]
	v_mfma_f32_16x16x32_bf16 v[40:43], v[164:167], v[188:191], v[40:43]
	v_mfma_f32_16x16x32_bf16 v[36:39], v[172:175], v[188:191], v[36:39]
	v_mfma_f32_16x16x32_bf16 v[24:27], v[164:167], v[196:199], v[24:27]
	v_mfma_f32_16x16x32_bf16 v[20:23], v[172:175], v[196:199], v[20:23]
	v_mfma_f32_16x16x32_bf16 v[8:11], v[164:167], v[208:211], v[8:11]
	v_mfma_f32_16x16x32_bf16 v[4:7], v[172:175], v[208:211], v[4:7]
	s_setprio 0
	s_barrier
	s_add_i32 s81, 0, 0x18000
	s_add_i32 s82, 0, 0x1c000
	v_add_u32_e32 v156, s81, v149
	v_add_u32_e32 v172, s82, v149
	ds_read_b128 v[140:143], v156
	ds_read_b128 v[144:147], v156 offset:1024
	ds_read_b128 v[152:155], v156 offset:2048
	ds_read_b128 v[156:159], v156 offset:3072
	ds_read_b128 v[160:163], v172
	ds_read_b128 v[164:167], v172 offset:1024
	ds_read_b128 v[168:171], v172 offset:2048
	ds_read_b128 v[172:175], v172 offset:3072
	s_add_u32 s50, s50, 0x80000
	s_addc_u32 s51, s51, 0
	s_mov_b32 m0, s60
	s_nop 0
	global_load_lds_dwordx4 v[216:217], off
	s_mov_b32 m0, s61
	v_lshl_add_u64 v[218:219], s[50:51], 0, v[134:135]
	ds_read_b128 v[176:179], v151 offset:32768
	ds_read_b128 v[180:183], v151 offset:33792
	ds_read_b128 v[184:187], v151 offset:34816
	ds_read_b128 v[188:191], v151 offset:35840
	ds_read_b128 v[192:195], v151 offset:36864
	ds_read_b128 v[196:199], v151 offset:37888
	ds_read_b128 v[204:207], v151 offset:38912
	ds_read_b128 v[208:211], v151 offset:39936
	global_load_lds_dwordx4 v[218:219], off
	v_lshl_add_u64 v[218:219], s[50:51], 0, v[132:133]
	s_mov_b32 m0, s70
	s_nop 0
	global_load_lds_dwordx4 v[218:219], off
	s_waitcnt vmcnt(8)
	s_waitcnt lgkmcnt(0)
	s_barrier
	s_setprio 1
	s_waitcnt lgkmcnt(0)
	v_mfma_f32_16x16x32_bf16 v[128:131], v[140:143], v[176:179], v[128:131]
	v_mfma_f32_16x16x32_bf16 v[124:127], v[152:155], v[176:179], v[124:127]
	v_mfma_f32_16x16x32_bf16 v[112:115], v[140:143], v[184:187], v[112:115]
	v_mfma_f32_16x16x32_bf16 v[108:111], v[152:155], v[184:187], v[108:111]
	v_mfma_f32_16x16x32_bf16 v[96:99], v[140:143], v[192:195], v[96:99]
	v_mfma_f32_16x16x32_bf16 v[92:95], v[152:155], v[192:195], v[92:95]
	v_mfma_f32_16x16x32_bf16 v[80:83], v[140:143], v[204:207], v[80:83]
	v_mfma_f32_16x16x32_bf16 v[76:79], v[152:155], v[204:207], v[76:79]
	v_mfma_f32_16x16x32_bf16 v[128:131], v[144:147], v[180:183], v[128:131]
	v_mfma_f32_16x16x32_bf16 v[124:127], v[156:159], v[180:183], v[124:127]
	v_mfma_f32_16x16x32_bf16 v[112:115], v[144:147], v[188:191], v[112:115]
	v_mfma_f32_16x16x32_bf16 v[108:111], v[156:159], v[188:191], v[108:111]
	v_mfma_f32_16x16x32_bf16 v[96:99], v[144:147], v[196:199], v[96:99]
	v_mfma_f32_16x16x32_bf16 v[92:95], v[156:159], v[196:199], v[92:95]
	v_mfma_f32_16x16x32_bf16 v[80:83], v[144:147], v[208:211], v[80:83]
	v_mfma_f32_16x16x32_bf16 v[76:79], v[156:159], v[208:211], v[76:79]
	s_setprio 0
	s_setprio 1
	v_mfma_f32_16x16x32_bf16 v[120:123], v[160:163], v[176:179], v[120:123]
	v_mfma_f32_16x16x32_bf16 v[116:119], v[168:171], v[176:179], v[116:119]
	v_mfma_f32_16x16x32_bf16 v[104:107], v[160:163], v[184:187], v[104:107]
	v_mfma_f32_16x16x32_bf16 v[100:103], v[168:171], v[184:187], v[100:103]
	v_mfma_f32_16x16x32_bf16 v[88:91], v[160:163], v[192:195], v[88:91]
	v_mfma_f32_16x16x32_bf16 v[84:87], v[168:171], v[192:195], v[84:87]
	v_mfma_f32_16x16x32_bf16 v[72:75], v[160:163], v[204:207], v[72:75]
	v_mfma_f32_16x16x32_bf16 v[68:71], v[168:171], v[204:207], v[68:71]
	v_mfma_f32_16x16x32_bf16 v[120:123], v[164:167], v[180:183], v[120:123]
	v_mfma_f32_16x16x32_bf16 v[116:119], v[172:175], v[180:183], v[116:119]
	v_mfma_f32_16x16x32_bf16 v[104:107], v[164:167], v[188:191], v[104:107]
	v_mfma_f32_16x16x32_bf16 v[100:103], v[172:175], v[188:191], v[100:103]
	v_mfma_f32_16x16x32_bf16 v[88:91], v[164:167], v[196:199], v[88:91]
	v_mfma_f32_16x16x32_bf16 v[84:87], v[172:175], v[196:199], v[84:87]
	v_mfma_f32_16x16x32_bf16 v[72:75], v[164:167], v[208:211], v[72:75]
	v_mfma_f32_16x16x32_bf16 v[68:71], v[172:175], v[208:211], v[68:71]
	s_setprio 0
	s_barrier
	s_add_i32 s50, s81, s52
	v_lshl_add_u64 v[200:201], v[200:201], 0, s[12:13]
	s_mov_b32 m0, s50
	ds_read_b128 v[176:179], v151 offset:49152
	ds_read_b128 v[180:183], v151 offset:50176
	ds_read_b128 v[184:187], v151 offset:51200
	ds_read_b128 v[188:191], v151 offset:52224
	ds_read_b128 v[192:195], v151 offset:53248
	ds_read_b128 v[196:199], v151 offset:54272
	ds_read_b128 v[204:207], v151 offset:55296
	ds_read_b128 v[208:211], v151 offset:56320
	global_load_lds_dwordx4 v[200:201], off
	s_add_i32 m0, s50, 0x2000
	s_add_u32 s48, s48, 0x80080
	v_lshl_add_u64 v[200:201], v[212:213], 0, s[12:13]
	s_addc_u32 s49, s49, 0
	s_add_i32 s50, s82, s52
	global_load_lds_dwordx4 v[200:201], off
	v_lshl_add_u64 v[200:201], s[48:49], 0, v[2:3]
	s_mov_b32 m0, s50
	s_nop 0
	global_load_lds_dwordx4 v[200:201], off
	v_lshl_add_u64 v[200:201], s[48:49], 0, v[0:1]
	s_add_i32 m0, s50, 0x2000
	s_nop 0
	global_load_lds_dwordx4 v[200:201], off
	v_lshl_add_u64 v[200:201], v[214:215], 0, s[12:13]
	s_mov_b32 m0, s71
	s_nop 0
	global_load_lds_dwordx4 v[200:201], off


	s_waitcnt vmcnt(7)
	s_waitcnt lgkmcnt(0)
	s_barrier
	s_setprio 1
	s_waitcnt lgkmcnt(0)
	v_mfma_f32_16x16x32_bf16 v[64:67], v[140:143], v[176:179], v[64:67]
	v_mfma_f32_16x16x32_bf16 v[60:63], v[152:155], v[176:179], v[60:63]
	v_mfma_f32_16x16x32_bf16 v[48:51], v[140:143], v[184:187], v[48:51]
	v_mfma_f32_16x16x32_bf16 v[44:47], v[152:155], v[184:187], v[44:47]
	v_mfma_f32_16x16x32_bf16 v[32:35], v[140:143], v[192:195], v[32:35]
	v_mfma_f32_16x16x32_bf16 v[28:31], v[152:155], v[192:195], v[28:31]
	v_mfma_f32_16x16x32_bf16 v[16:19], v[140:143], v[204:207], v[16:19]
	v_mfma_f32_16x16x32_bf16 v[12:15], v[152:155], v[204:207], v[12:15]
	v_mfma_f32_16x16x32_bf16 v[64:67], v[144:147], v[180:183], v[64:67]
	v_mfma_f32_16x16x32_bf16 v[60:63], v[156:159], v[180:183], v[60:63]
	v_mfma_f32_16x16x32_bf16 v[48:51], v[144:147], v[188:191], v[48:51]
	v_mfma_f32_16x16x32_bf16 v[44:47], v[156:159], v[188:191], v[44:47]
	v_mfma_f32_16x16x32_bf16 v[32:35], v[144:147], v[196:199], v[32:35]
	v_mfma_f32_16x16x32_bf16 v[28:31], v[156:159], v[196:199], v[28:31]
	v_mfma_f32_16x16x32_bf16 v[16:19], v[144:147], v[208:211], v[16:19]
	v_mfma_f32_16x16x32_bf16 v[12:15], v[156:159], v[208:211], v[12:15]
	s_setprio 0
	s_setprio 1
	v_mfma_f32_16x16x32_bf16 v[56:59], v[160:163], v[176:179], v[56:59]
	v_mfma_f32_16x16x32_bf16 v[52:55], v[168:171], v[176:179], v[52:55]
	v_mfma_f32_16x16x32_bf16 v[40:43], v[160:163], v[184:187], v[40:43]
	v_mfma_f32_16x16x32_bf16 v[36:39], v[168:171], v[184:187], v[36:39]
	v_mfma_f32_16x16x32_bf16 v[24:27], v[160:163], v[192:195], v[24:27]
	v_mfma_f32_16x16x32_bf16 v[20:23], v[168:171], v[192:195], v[20:23]
	v_mfma_f32_16x16x32_bf16 v[8:11], v[160:163], v[204:207], v[8:11]
	v_mfma_f32_16x16x32_bf16 v[4:7], v[168:171], v[204:207], v[4:7]
	v_mfma_f32_16x16x32_bf16 v[56:59], v[164:167], v[180:183], v[56:59]
	v_mfma_f32_16x16x32_bf16 v[52:55], v[172:175], v[180:183], v[52:55]
	v_mfma_f32_16x16x32_bf16 v[40:43], v[164:167], v[188:191], v[40:43]
	v_mfma_f32_16x16x32_bf16 v[36:39], v[172:175], v[188:191], v[36:39]
	v_mfma_f32_16x16x32_bf16 v[24:27], v[164:167], v[196:199], v[24:27]
	v_mfma_f32_16x16x32_bf16 v[20:23], v[172:175], v[196:199], v[20:23]
	v_mfma_f32_16x16x32_bf16 v[8:11], v[164:167], v[208:211], v[8:11]
	v_mfma_f32_16x16x32_bf16 v[4:7], v[172:175], v[208:211], v[4:7]
	s_setprio 0
	s_barrier
	s_add_i32 s80, s80, 2
	s_add_u32 s46, s46, 0x100
	s_addc_u32 s47, s47, 0
	s_add_u32 s78, s78, 0x100
	s_addc_u32 s79, s79, 0
	s_cmp_gt_u32 s80, 29
	s_cbranch_scc0 .LBB0_685
	v_readlane_b32 s78, v254, 48
	v_readlane_b32 s80, v254, 50
	s_and_b64 vcc, exec, s[10:11]
	v_readlane_b32 s79, v254, 49
	v_readlane_b32 s81, v254, 51
	v_readlane_b32 s76, v254, 62
	v_readlane_b32 s77, v254, 63
	s_cbranch_vccz .LBB0_688
	s_barrier
